# v25 + wave reductions (xor 16/32) in the w_o / down epilogues and one GLA chunk: ds_bpermute + LDS wait replaced by v_permlane16/32_swap register exchanges (32 sites)
# baseline (speedup 1.0000x reference)
; #define LAS __attribute__((address_space(3)))
; #define MFMA16(a, b, c) __builtin_amdgcn_mfma_f32_16x16x32_bf16((a), (b), (c), 0, 0, 0)
; __device__ __forceinline__ u32x2 f32_to_bf4(f32x4 v) { u32x2 w; w.x = cvtpk(v[0], v[1]); w.y = cvtpk(v[2], v[3]); return w; }
; template <bool FULL> __device__ __forceinline__ void gla_unit(LAS unsigned char* lds, const MixBufs& B, int b, int h, int seg, int tid) {
;     ...
;                     if (ti >= sj) af = MFMA16(frag_row(lds + okf, GP64, 16 * sj, 32 * ks, lane), frag_row(lds + G_QF, GP64, 16 * ti, 32 * ks, lane), af);
;                     if (ti <= sj) ab = MFMA16(frag_row(lds + G_KB, GP64, 16 * sj, 32 * ks, lane), frag_row(lds + G_QB, GP64, 16 * ti, 32 * ks, lane), ab);
;                 }
;                 f32x4 p;
; #pragma unroll
;                 for (int i = 0; i < 4; ++i) p[i] = (16 * ti + c >= 16 * sj + 4 * g + i) ? af[i] : ab[i];
;                 *(LAS u32x2*)(lds + G_P + (16 * ti + c) * GP64 + (16 * sj + 4 * g) * 2) = f32_to_bf4(p); }
;             __syncthreads();
;             f32x4 o[4];
; #pragma unroll
;             for (int j = 0; j < 4; ++j) o[j] = (f32x4){0.f, 0.f, 0.f, 0.f};
; #pragma unroll
;             for (int ks = 0; ks < 2; ++ks) { const bf16x8 pf = frag_row(lds + G_P, GP64, 16 * ti, 32 * ks, lane);
; #pragma unroll
;                 for (int j = 0; j < 4; ++j) o[j] = MFMA16(vfr[j][ks], pf, o[j]); }
; #pragma unroll
;             for (int kk = 0; kk < 2; ++kk) { const bf16x8 qf = frag_row(lds + G_QF, GP64, 16 * ti, 32 * kk, lane);
; #pragma unroll
;                 for (int j = 0; j < 4; ++j) o[j] = MFMA16(frag_row(lds + G_ST, GP64, 16 * (4 * vh + j), 32 * kk, lane), qf, o[j]); }
;             float ss = 0.f;
; #pragma unroll
;             for (int j = 0; j < 4; ++j) ss += (o[j][0] * o[j][0] + o[j][1] * o[j][1]) + (o[j][2] * o[j][2] + o[j][3] * o[j][3]);
;             ss += __shfl_xor(ss, 16); ss += __shfl_xor(ss, 32);
;             if (g == 0) SSQ[vh * 64 + 16 * ti + c] = ss;
.LBB0_717:
	v_or_b32_e32 v126, s22, v184
	v_cmp_lt_i32_e64 s[22:23], v122, v126
	v_cmp_gt_i32_e64 s[24:25], v122, v126
	s_lshl_b32 s4, s35, 5
	s_nop 3
	v_cndmask_b32_e64 v112, v112, v116, s[22:23]
	v_or_b32_e32 v116, 2, v126
	v_cmp_lt_i32_e64 s[26:27], v122, v116
	v_or_b32_e32 v116, 3, v126
	v_cmp_lt_i32_e64 s[28:29], v122, v116
	v_cndmask_b32_e64 v113, v117, v113, s[24:25]
	v_cndmask_b32_e64 v114, v114, v118, s[26:27]
	v_cndmask_b32_e64 v115, v115, v119, s[28:29]
	v_cvt_pk_bf16_f32 v112, v112, v113
	v_cvt_pk_bf16_f32 v113, v114, v115
	v_add_u32_e32 v201, s4, v120
	ds_write_b64 v201, v[112:113] offset:54272
	s_waitcnt lgkmcnt(0)
	s_barrier
	ds_read_b128 v[112:115], v189 offset:54272
	ds_read_b128 v[116:119], v189 offset:54336
	v_add_u32_e32 v199, v125, v124
	ds_read_b128 v[218:221], v199 offset:63488
	s_waitcnt lgkmcnt(2)
	v_mfma_f32_16x16x32_bf16 v[194:197], v[100:103], v[112:115], 0
	v_add_u32_e32 v193, v125, v121
	v_add_u32_e32 v120, 0xf840, v125
	v_add_u32_e32 v121, v120, v121
	v_mfma_f32_16x16x32_bf16 v[210:213], v[96:99], v[112:115], 0
	v_add_u32_e32 v122, v120, v123
	v_add_u32_e32 v120, v120, v153
	v_xor_b32_e32 v133, 16, v183
	v_mfma_f32_16x16x32_bf16 v[214:217], v[104:107], v[112:115], 0
	s_lshl_b32 s35, s79, 2
	s_add_i32 s83, s35, 0
	s_add_i32 s35, s83, 0x14100
	v_mfma_f32_16x16x32_bf16 v[112:115], v[108:111], v[112:115], 0
	s_and_b32 s34, s34, 0xffffff00
	v_cmp_gt_u32_e64 s[4:5], 16, v176
	s_waitcnt lgkmcnt(1)
	v_mfma_f32_16x16x32_bf16 v[194:197], v[92:95], v[116:119], v[194:197]
	v_mfma_f32_16x16x32_bf16 v[210:213], v[88:91], v[116:119], v[210:213]
	v_mfma_f32_16x16x32_bf16 v[214:217], v[84:87], v[116:119], v[214:217]
	v_mfma_f32_16x16x32_bf16 v[112:115], v[80:83], v[116:119], v[112:115]
	ds_read_b128 v[116:119], v193 offset:63488
	ds_read_b128 v[222:225], v189
	ds_read_b128 v[226:229], v189 offset:64
	ds_read_b128 v[230:233], v199 offset:63552
	s_waitcnt lgkmcnt(2)
	v_mfma_f32_16x16x32_bf16 v[218:221], v[218:221], v[222:225], v[194:197]
	s_nop 2
	v_add_u32_e32 v197, v125, v123
	v_add_u32_e32 v195, v125, v153
	ds_read_b128 v[234:237], v197 offset:63488
	v_mfma_f32_16x16x32_bf16 v[116:119], v[116:119], v[222:225], v[210:213]
	s_nop 2
	ds_read_b128 v[210:213], v195 offset:63488
	s_waitcnt lgkmcnt(0)
	v_mfma_f32_16x16x32_bf16 v[112:115], v[210:213], v[222:225], v[112:115]
	ds_read_b128 v[210:213], v122
	v_mfma_f32_16x16x32_bf16 v[214:217], v[234:237], v[222:225], v[214:217]
	ds_read_b128 v[234:237], v121
	v_mfma_f32_16x16x32_bf16 v[124:127], v[230:233], v[226:229], v[218:221]
	s_nop 2
	ds_read_b128 v[218:221], v120
	v_and_b32_e32 v121, 64, v183
	v_add_u32_e32 v143, 64, v121
	s_waitcnt lgkmcnt(1)
	v_mfma_f32_16x16x32_bf16 v[120:123], v[234:237], v[226:229], v[116:119]
	v_cmp_lt_i32_e32 vcc, v133, v143
	v_mul_f32_e32 v153, v127, v127
	v_fmac_f32_e32 v153, v126, v126
	v_cndmask_b32_e32 v116, v183, v133, vcc
	v_xor_b32_e32 v133, 32, v183
	v_cmp_lt_i32_e32 vcc, v133, v143
	v_mul_f32_e32 v143, v125, v125
	v_lshlrev_b32_e32 v190, 2, v116
	v_mfma_f32_16x16x32_bf16 v[116:119], v[210:213], v[226:229], v[214:217]
	v_fmac_f32_e32 v143, v124, v124
	v_add_f32_e32 v143, v143, v153
	v_mul_f32_e32 v153, v121, v121
	v_mul_f32_e32 v191, v123, v123
	v_fmac_f32_e32 v153, v120, v120
	v_fmac_f32_e32 v191, v122, v122
	s_waitcnt lgkmcnt(0)
	v_mfma_f32_16x16x32_bf16 v[112:115], v[218:221], v[226:229], v[112:115]
	v_add_f32_e32 v153, v153, v191
	v_add_f32_e32 v143, v143, v153
	v_mul_f32_e32 v153, v117, v117
	v_mul_f32_e32 v191, v119, v119
	v_fmac_f32_e32 v153, v116, v116
	v_fmac_f32_e32 v191, v118, v118
	v_add_f32_e32 v153, v153, v191
	v_add_f32_e32 v143, v143, v153
	v_mul_f32_e32 v153, v113, v113
	v_mul_f32_e32 v191, v115, v115
	v_fmac_f32_e32 v153, v112, v112
	v_fmac_f32_e32 v191, v114, v114
	v_add_f32_e32 v153, v153, v191
	v_add_f32_e32 v143, v143, v153
	v_mov_b32_e32 v153, v143
	s_nop 1
	v_permlane16_swap_b32_e32 v143, v153
	v_cndmask_b32_e32 v133, v183, v133, vcc
	v_lshlrev_b32_e32 v194, 2, v133
	v_lshl_add_u32 v191, v177, 2, s35
	v_add_u32_e32 v196, s34, v191
	s_waitcnt lgkmcnt(0)
	v_add_f32_e32 v133, v143, v153
	v_mov_b32_e32 v143, v133
	s_nop 1
	v_permlane32_swap_b32_e32 v133, v143
	s_and_saveexec_b64 s[34:35], s[4:5]
	s_cbranch_execz .LBB0_719
	s_waitcnt lgkmcnt(0)
	v_add_f32_e32 v133, v133, v143
	ds_write_b32 v196, v133

; #define PG8_LAS __attribute__((address_space(3)))
;     __device__ __forceinline__ bool run(const f32x4 (&v)[2][2][4][2], const Unit& u, int wr, int wc, int fr, int fq, PG8_LAS unsigned char* lds, int wid, int lane) const {
;     ...
; #pragma unroll
;         for (int ai = 0; ai < 2; ++ai)
; #pragma unroll
;             for (int m = 0; m < 4; ++m) {
;                 float q = 0.f;
; #pragma unroll
;                 for (int bj = 0; bj < 2; ++bj)
; #pragma unroll
;                     for (int n = 0; n < 2; ++n) { const f32x4 d = v[ai][bj][m][n]; q += (d[0] * d[0] + d[1] * d[1]) + (d[2] * d[2] + d[3] * d[3]); }
;                 q += __shfl_xor(q, 16); q += __shfl_xor(q, 32);
;                 if (fq == 0) P[(ai * HALF + wr * 64 + m * 16 + fr) * 4 + wc] = q;
;             }
;     __device__ __forceinline__ void fused(f32x4 (&acc)[2][2][4][2], const Unit& u, int wr, int wc, int fr, int fq, PG8_LAS unsigned char* lds, int wid, int lane) const {
;         const PG8_LAS float* S = (const PG8_LAS float*)(lds + 8192);
;         PG8_LAS float* P = (PG8_LAS float*)lds;
;         const int col0 = u.pn * BM + wc * CWS + 8 * fq;
;         u32x4 pre[2][4][2]; float xsr[2][4];
; #pragma unroll
;         for (int ai = 0; ai < 2; ++ai)
; #pragma unroll
;             for (int m = 0; m < 4; ++m) { const size_t row = (size_t)(u.pm * BM + ai * HALF + wr * 64 + m * 16 + fr), off = row * ldc + col0;
;                 xsr[ai][m] = xs[row];
; #pragma unroll
;                 for (int bj = 0; bj < 2; ++bj) pre[ai][m][bj] = *(const u32x4*)(xn + off + bj * CBS); }
;         f32x4 gq[2][2];
; #pragma unroll
;         for (int bj = 0; bj < 2; ++bj) { gq[bj][0] = *(const f32x4*)(gain1 + col0 + bj * CBS); gq[bj][1] = *(const f32x4*)(gain1 + col0 + bj * CBS + 4); }
.LBB0_1185:
	s_add_u32 s6, s88, 0x2300000
	s_addc_u32 s7, s89, 0
	s_lshl_b32 s8, s0, 8
	s_lshl_b32 s9, s15, 6
	v_lshrrev_b32_e32 v124, 1, v215
	s_or_b32 s8, s8, s9
	s_lshl_b32 s26, s14, 8
	v_and_or_b32 v210, v124, 24, s8
	s_add_i32 s8, s26, s64
	v_or_b32_e32 v124, s8, v223
	v_readlane_b32 s8, v241, 53
	v_ashrrev_i32_e32 v125, 31, v124
	v_ashrrev_i32_e32 v211, 31, v210
	v_readlane_b32 s9, v241, 54
	v_lshl_add_u64 v[128:129], v[124:125], 2, s[6:7]
	s_barrier
	v_lshl_add_u64 v[126:127], v[210:211], 1, s[8:9]
	global_load_dword v226, v[128:129], off
	v_lshlrev_b64 v[128:129], 11, v[124:125]
	v_lshl_add_u64 v[128:129], v[126:127], 0, v[128:129]
	global_load_dwordx4 v[206:209], v[128:129], off
	global_load_dwordx4 v[202:205], v[128:129], off offset:64
	v_or_b32_e32 v128, 16, v124
	v_ashrrev_i32_e32 v129, 31, v128
	v_lshl_add_u64 v[130:131], v[128:129], 2, s[6:7]
	v_lshlrev_b64 v[128:129], 11, v[128:129]
	v_lshl_add_u64 v[128:129], v[126:127], 0, v[128:129]
	global_load_dword v224, v[130:131], off
	global_load_dwordx4 v[198:201], v[128:129], off
	global_load_dwordx4 v[194:197], v[128:129], off offset:64
	v_or_b32_e32 v128, 32, v124
	v_ashrrev_i32_e32 v129, 31, v128
	v_lshl_add_u64 v[130:131], v[128:129], 2, s[6:7]
	v_lshlrev_b64 v[128:129], 11, v[128:129]
	v_lshl_add_u64 v[128:129], v[126:127], 0, v[128:129]
	global_load_dword v222, v[130:131], off
	global_load_dwordx4 v[190:193], v[128:129], off
	global_load_dwordx4 v[186:189], v[128:129], off offset:64
	v_or_b32_e32 v128, 48, v124
	v_ashrrev_i32_e32 v129, 31, v128
	v_lshl_add_u64 v[130:131], v[128:129], 2, s[6:7]
	v_lshlrev_b64 v[128:129], 11, v[128:129]
	v_lshl_add_u64 v[128:129], v[126:127], 0, v[128:129]
	global_load_dword v220, v[130:131], off
	global_load_dwordx4 v[182:185], v[128:129], off
	global_load_dwordx4 v[178:181], v[128:129], off offset:64
	v_add_u32_e32 v128, 0x80, v124
	v_ashrrev_i32_e32 v129, 31, v128
	v_lshl_add_u64 v[130:131], v[128:129], 2, s[6:7]
	v_lshlrev_b64 v[128:129], 11, v[128:129]
	v_lshl_add_u64 v[128:129], v[126:127], 0, v[128:129]
	global_load_dword v218, v[130:131], off
	global_load_dwordx4 v[174:177], v[128:129], off
	global_load_dwordx4 v[170:173], v[128:129], off offset:64
	v_add_u32_e32 v128, 0x90, v124
	v_ashrrev_i32_e32 v129, 31, v128
	v_lshl_add_u64 v[130:131], v[128:129], 2, s[6:7]
	v_lshlrev_b64 v[128:129], 11, v[128:129]
	v_lshl_add_u64 v[128:129], v[126:127], 0, v[128:129]
	global_load_dword v216, v[130:131], off
	global_load_dwordx4 v[166:169], v[128:129], off
	global_load_dwordx4 v[162:165], v[128:129], off offset:64
	v_add_u32_e32 v128, 0xa0, v124
	v_ashrrev_i32_e32 v129, 31, v128
	v_readlane_b32 s36, v241, 18
	v_lshl_add_u64 v[130:131], v[128:129], 2, s[6:7]
	v_lshlrev_b64 v[128:129], 11, v[128:129]
	v_add_u32_e32 v124, 0xb0, v124
	v_readlane_b32 s40, v241, 22
	v_readlane_b32 s41, v241, 23
	v_lshl_add_u64 v[128:129], v[126:127], 0, v[128:129]
	v_ashrrev_i32_e32 v125, 31, v124
	v_mov_b32_e32 v122, s40
	v_mov_b32_e32 v123, s41
	global_load_dword v214, v[130:131], off
	global_load_dwordx4 v[158:161], v[128:129], off
	global_load_dwordx4 v[154:157], v[128:129], off offset:64
	v_lshl_add_u64 v[128:129], v[124:125], 2, s[6:7]
	v_lshlrev_b64 v[124:125], 11, v[124:125]
	v_lshl_add_u64 v[124:125], v[126:127], 0, v[124:125]
	v_lshl_add_u64 v[126:127], v[210:211], 2, v[122:123]
	global_load_dword v212, v[128:129], off
	global_load_dwordx4 v[142:145], v[124:125], off
	global_load_dwordx4 v[130:133], v[124:125], off offset:64
	global_load_dwordx4 v[134:137], v[126:127], off offset:16
	global_load_dwordx4 v[138:141], v[126:127], off
	s_nop 0
	global_load_dwordx4 v[122:125], v[126:127], off offset:144
	s_nop 0
	global_load_dwordx4 v[126:129], v[126:127], off offset:128
	v_mul_f32_e32 v225, v151, v151
	v_mul_f32_e32 v227, v153, v153
	v_fmac_f32_e32 v225, v150, v150
	v_fmac_f32_e32 v227, v152, v152
	v_add_f32_e32 v225, v225, v227
	v_mul_f32_e32 v227, v147, v147
	v_mul_f32_e32 v228, v149, v149
	v_fmac_f32_e32 v227, v146, v146
	v_fmac_f32_e32 v228, v148, v148
	v_add_f32_e32 v227, v227, v228
	v_mbcnt_lo_u32_b32 v217, -1, 0
	v_add_f32_e32 v225, v227, v225
	v_mul_f32_e32 v227, v119, v119
	v_mul_f32_e32 v228, v121, v121
	v_mbcnt_hi_u32_b32 v219, -1, v217
	v_fmac_f32_e32 v227, v118, v118
	v_fmac_f32_e32 v228, v120, v120
	v_and_b32_e32 v221, 64, v219
	v_add_f32_e32 v227, v227, v228
	v_xor_b32_e32 v217, 16, v219
	v_add_u32_e32 v221, 64, v221
	v_add_f32_e32 v225, v227, v225
	v_mul_f32_e32 v227, v115, v115
	v_mul_f32_e32 v228, v117, v117
	v_cmp_lt_i32_e32 vcc, v217, v221
	v_fmac_f32_e32 v227, v114, v114
	v_fmac_f32_e32 v228, v116, v116
	v_cndmask_b32_e32 v217, v219, v217, vcc
	v_add_f32_e32 v227, v227, v228
	v_lshlrev_b32_e32 v217, 2, v217
	v_add_f32_e32 v225, v227, v225
	v_mov_b32_e32 v227, v225
	s_nop 1
	v_permlane16_swap_b32_e32 v225, v227
	v_xor_b32_e32 v228, 32, v219
	v_cmp_lt_i32_e32 vcc, v228, v221
	s_lshl_b32 s8, s15, 2
	s_add_i32 s27, s8, 0
	v_cndmask_b32_e32 v219, v219, v228, vcc
	v_lshlrev_b32_e32 v221, 2, v219
	s_waitcnt lgkmcnt(0)
	v_add_f32_e32 v225, v225, v227
	v_mov_b32_e32 v227, v225
	s_nop 1
	v_permlane32_swap_b32_e32 v225, v227
	v_and_b32_e32 v219, 63, v215
	v_cmp_gt_u32_e64 s[6:7], 16, v219
	v_readlane_b32 s37, v241, 19
	v_readlane_b32 s38, v241, 20
	v_readlane_b32 s39, v241, 21
	v_readlane_b32 s42, v241, 24
	v_readlane_b32 s43, v241, 25
	v_readlane_b32 s44, v241, 26
	v_readlane_b32 s45, v241, 27
	v_readlane_b32 s46, v241, 28
	v_readlane_b32 s47, v241, 29
	v_readlane_b32 s48, v241, 30
	v_readlane_b32 s49, v241, 31
	v_readlane_b32 s50, v241, 32
	v_readlane_b32 s51, v241, 33
	s_and_saveexec_b64 s[8:9], s[6:7]
	s_cbranch_execz .LBB0_1187
	s_lshl_b32 s10, s31, 10
	s_add_i32 s10, s27, s10
	s_waitcnt lgkmcnt(0)
	v_add_f32_e32 v225, v225, v227
	v_lshl_add_u32 v227, v223, 4, s10
	ds_write_b32 v227, v225
;     __device__ __forceinline__ bool run(const f32x4 (&v)[2][2][4][2], const Unit& u, int wr, int wc, int fr, int fq, PG8_LAS unsigned char* lds, int wid, int lane) const {
;     ...
; #pragma unroll
;         for (int ai = 0; ai < 2; ++ai)
; #pragma unroll
;             for (int m = 0; m < 4; ++m) {
;                 float q = 0.f;
; #pragma unroll
;                 for (int bj = 0; bj < 2; ++bj)
; #pragma unroll
;                     for (int n = 0; n < 2; ++n) { const f32x4 d = v[ai][bj][m][n]; q += (d[0] * d[0] + d[1] * d[1]) + (d[2] * d[2] + d[3] * d[3]); }
;                 q += __shfl_xor(q, 16); q += __shfl_xor(q, 32);
;                 if (fq == 0) P[(ai * HALF + wr * 64 + m * 16 + fr) * 4 + wc] = q;
;             }
.LBB0_1187:
	s_or_b64 exec, exec, s[8:9]
	v_mul_f32_e32 v225, v111, v111
	s_waitcnt lgkmcnt(0)
	v_mul_f32_e32 v227, v113, v113
	v_fmac_f32_e32 v225, v110, v110
	v_fmac_f32_e32 v227, v112, v112
	v_add_f32_e32 v225, v225, v227
	v_mul_f32_e32 v227, v107, v107
	v_mul_f32_e32 v228, v109, v109
	v_fmac_f32_e32 v227, v106, v106
	v_fmac_f32_e32 v228, v108, v108
	v_add_f32_e32 v227, v227, v228
	v_add_f32_e32 v225, v227, v225
	v_mul_f32_e32 v227, v103, v103
	v_mul_f32_e32 v228, v105, v105
	v_fmac_f32_e32 v227, v102, v102
	v_fmac_f32_e32 v228, v104, v104
	v_add_f32_e32 v227, v227, v228
	v_add_f32_e32 v225, v227, v225
	v_mul_f32_e32 v227, v99, v99
	v_mul_f32_e32 v228, v101, v101
	v_fmac_f32_e32 v227, v98, v98
	v_fmac_f32_e32 v228, v100, v100
	v_add_f32_e32 v227, v227, v228
	v_add_f32_e32 v225, v227, v225
	v_mov_b32_e32 v227, v225
	s_nop 1
	v_permlane16_swap_b32_e32 v225, v227
	s_waitcnt lgkmcnt(0)
	v_add_f32_e32 v225, v225, v227
	v_mov_b32_e32 v227, v225
	s_nop 1
	v_permlane32_swap_b32_e32 v225, v227
	s_and_saveexec_b64 s[8:9], s[6:7]
	s_cbranch_execz .LBB0_1189
	s_lshl_b32 s10, s31, 10
	s_add_i32 s10, s27, s10
	s_waitcnt lgkmcnt(0)
	v_add_f32_e32 v225, v225, v227
	v_lshl_add_u32 v227, v223, 4, s10
	ds_write_b32 v227, v225 offset:256
.LBB0_1189:
	s_or_b64 exec, exec, s[8:9]
	v_mul_f32_e32 v225, v95, v95
	s_waitcnt lgkmcnt(0)
	v_mul_f32_e32 v227, v97, v97
	v_fmac_f32_e32 v225, v94, v94
	v_fmac_f32_e32 v227, v96, v96
	v_add_f32_e32 v225, v225, v227
	v_mul_f32_e32 v227, v91, v91
	v_mul_f32_e32 v228, v93, v93
	v_fmac_f32_e32 v227, v90, v90
	v_fmac_f32_e32 v228, v92, v92
	v_add_f32_e32 v227, v227, v228
	v_add_f32_e32 v225, v227, v225
	v_mul_f32_e32 v227, v87, v87
	v_mul_f32_e32 v228, v89, v89
	v_fmac_f32_e32 v227, v86, v86
	v_fmac_f32_e32 v228, v88, v88
	v_add_f32_e32 v227, v227, v228
	v_add_f32_e32 v225, v227, v225
	v_mul_f32_e32 v227, v83, v83
	v_mul_f32_e32 v228, v85, v85
	v_fmac_f32_e32 v227, v82, v82
	v_fmac_f32_e32 v228, v84, v84
	v_add_f32_e32 v227, v227, v228
	v_add_f32_e32 v225, v227, v225
	v_mov_b32_e32 v227, v225
	s_nop 1
	v_permlane16_swap_b32_e32 v225, v227
	s_waitcnt lgkmcnt(0)
	v_add_f32_e32 v225, v225, v227
	v_mov_b32_e32 v227, v225
	s_nop 1
	v_permlane32_swap_b32_e32 v225, v227
	s_and_saveexec_b64 s[8:9], s[6:7]
	s_cbranch_execz .LBB0_1191
	s_lshl_b32 s10, s31, 10
	s_add_i32 s10, s27, s10
	s_waitcnt lgkmcnt(0)
	v_add_f32_e32 v225, v225, v227
	v_lshl_add_u32 v227, v223, 4, s10
	ds_write_b32 v227, v225 offset:512
.LBB0_1191:
	s_or_b64 exec, exec, s[8:9]
	v_mul_f32_e32 v225, v79, v79
	s_waitcnt lgkmcnt(0)
	v_mul_f32_e32 v227, v81, v81
	v_fmac_f32_e32 v225, v78, v78
	v_fmac_f32_e32 v227, v80, v80
	v_add_f32_e32 v225, v225, v227
	v_mul_f32_e32 v227, v75, v75
	v_mul_f32_e32 v228, v77, v77
	v_fmac_f32_e32 v227, v74, v74
	v_fmac_f32_e32 v228, v76, v76
	v_add_f32_e32 v227, v227, v228
	v_add_f32_e32 v225, v227, v225
	v_mul_f32_e32 v227, v71, v71
	v_mul_f32_e32 v228, v73, v73
	v_fmac_f32_e32 v227, v70, v70
	v_fmac_f32_e32 v228, v72, v72
	v_add_f32_e32 v227, v227, v228
	v_add_f32_e32 v225, v227, v225
	v_mul_f32_e32 v227, v67, v67
	v_mul_f32_e32 v228, v69, v69
	v_fmac_f32_e32 v227, v66, v66
	v_fmac_f32_e32 v228, v68, v68
	v_add_f32_e32 v227, v227, v228
	v_add_f32_e32 v225, v227, v225
	v_mov_b32_e32 v227, v225
	s_nop 1
	v_permlane16_swap_b32_e32 v225, v227
	s_waitcnt lgkmcnt(0)
	v_add_f32_e32 v225, v225, v227
	v_mov_b32_e32 v227, v225
	s_nop 1
	v_permlane32_swap_b32_e32 v225, v227
	s_and_saveexec_b64 s[8:9], s[6:7]
	s_cbranch_execz .LBB0_1193
	s_lshl_b32 s10, s31, 10
	s_add_i32 s10, s27, s10
	s_waitcnt lgkmcnt(0)
	v_add_f32_e32 v225, v225, v227
	v_lshl_add_u32 v227, v223, 4, s10
	ds_write_b32 v227, v225 offset:768
;     __device__ __forceinline__ bool run(const f32x4 (&v)[2][2][4][2], const Unit& u, int wr, int wc, int fr, int fq, PG8_LAS unsigned char* lds, int wid, int lane) const {
;     ...
; #pragma unroll
;         for (int ai = 0; ai < 2; ++ai)
; #pragma unroll
;             for (int m = 0; m < 4; ++m) {
;                 float q = 0.f;
; #pragma unroll
;                 for (int bj = 0; bj < 2; ++bj)
; #pragma unroll
;                     for (int n = 0; n < 2; ++n) { const f32x4 d = v[ai][bj][m][n]; q += (d[0] * d[0] + d[1] * d[1]) + (d[2] * d[2] + d[3] * d[3]); }
;                 q += __shfl_xor(q, 16); q += __shfl_xor(q, 32);
;                 if (fq == 0) P[(ai * HALF + wr * 64 + m * 16 + fr) * 4 + wc] = q;
;             }
.LBB0_1193:
	s_or_b64 exec, exec, s[8:9]
	v_mul_f32_e32 v225, v63, v63
	s_waitcnt lgkmcnt(0)
	v_mul_f32_e32 v227, v65, v65
	v_fmac_f32_e32 v225, v62, v62
	v_fmac_f32_e32 v227, v64, v64
	v_add_f32_e32 v225, v225, v227
	v_mul_f32_e32 v227, v59, v59
	v_mul_f32_e32 v228, v61, v61
	v_fmac_f32_e32 v227, v58, v58
	v_fmac_f32_e32 v228, v60, v60
	v_add_f32_e32 v227, v227, v228
	v_add_f32_e32 v225, v227, v225
	v_mul_f32_e32 v227, v55, v55
	v_mul_f32_e32 v228, v57, v57
	v_fmac_f32_e32 v227, v54, v54
	v_fmac_f32_e32 v228, v56, v56
	v_add_f32_e32 v227, v227, v228
	v_add_f32_e32 v225, v227, v225
	v_mul_f32_e32 v227, v51, v51
	v_mul_f32_e32 v228, v53, v53
	v_fmac_f32_e32 v227, v50, v50
	v_fmac_f32_e32 v228, v52, v52
	v_add_f32_e32 v227, v227, v228
	v_add_f32_e32 v225, v227, v225
	v_mov_b32_e32 v227, v225
	s_nop 1
	v_permlane16_swap_b32_e32 v225, v227
	s_waitcnt lgkmcnt(0)
	v_add_f32_e32 v225, v225, v227
	v_mov_b32_e32 v227, v225
	s_nop 1
	v_permlane32_swap_b32_e32 v225, v227
	s_and_saveexec_b64 s[8:9], s[6:7]
	s_cbranch_execz .LBB0_1195
	s_lshl_b32 s10, s31, 10
	s_add_i32 s10, s27, s10
	s_waitcnt lgkmcnt(0)
	v_add_f32_e32 v225, v225, v227
	v_lshl_add_u32 v227, v223, 4, s10
	ds_write_b32 v227, v225 offset:2048
.LBB0_1195:
	s_or_b64 exec, exec, s[8:9]
	v_mul_f32_e32 v225, v47, v47
	s_waitcnt lgkmcnt(0)
	v_mul_f32_e32 v227, v49, v49
	v_fmac_f32_e32 v225, v46, v46
	v_fmac_f32_e32 v227, v48, v48
	v_add_f32_e32 v225, v225, v227
	v_mul_f32_e32 v227, v43, v43
	v_mul_f32_e32 v228, v45, v45
	v_fmac_f32_e32 v227, v42, v42
	v_fmac_f32_e32 v228, v44, v44
	v_add_f32_e32 v227, v227, v228
	v_add_f32_e32 v225, v227, v225
	v_mul_f32_e32 v227, v39, v39
	v_mul_f32_e32 v228, v41, v41
	v_fmac_f32_e32 v227, v38, v38
	v_fmac_f32_e32 v228, v40, v40
	v_add_f32_e32 v227, v227, v228
	v_add_f32_e32 v225, v227, v225
	v_mul_f32_e32 v227, v35, v35
	v_mul_f32_e32 v228, v37, v37
	v_fmac_f32_e32 v227, v34, v34
	v_fmac_f32_e32 v228, v36, v36
	v_add_f32_e32 v227, v227, v228
	v_add_f32_e32 v225, v227, v225
	v_mov_b32_e32 v227, v225
	s_nop 1
	v_permlane16_swap_b32_e32 v225, v227
	s_waitcnt lgkmcnt(0)
	v_add_f32_e32 v225, v225, v227
	v_mov_b32_e32 v227, v225
	s_nop 1
	v_permlane32_swap_b32_e32 v225, v227
	s_and_saveexec_b64 s[8:9], s[6:7]
	s_cbranch_execz .LBB0_1197
	s_lshl_b32 s10, s31, 10
	s_add_i32 s10, s27, s10
	s_waitcnt lgkmcnt(0)
	v_add_f32_e32 v225, v225, v227
	v_lshl_add_u32 v227, v223, 4, s10
	ds_write_b32 v227, v225 offset:2304
.LBB0_1197:
	s_or_b64 exec, exec, s[8:9]
	v_mul_f32_e32 v225, v31, v31
	s_waitcnt lgkmcnt(0)
	v_mul_f32_e32 v227, v33, v33
	v_fmac_f32_e32 v225, v30, v30
	v_fmac_f32_e32 v227, v32, v32
	v_add_f32_e32 v225, v225, v227
	v_mul_f32_e32 v227, v27, v27
	v_mul_f32_e32 v228, v29, v29
	v_fmac_f32_e32 v227, v26, v26
	v_fmac_f32_e32 v228, v28, v28
	v_add_f32_e32 v227, v227, v228
	v_add_f32_e32 v225, v227, v225
	v_mul_f32_e32 v227, v23, v23
	v_mul_f32_e32 v228, v25, v25
	v_fmac_f32_e32 v227, v22, v22
	v_fmac_f32_e32 v228, v24, v24
	v_add_f32_e32 v227, v227, v228
	v_add_f32_e32 v225, v227, v225
	v_mul_f32_e32 v227, v19, v19
	v_mul_f32_e32 v228, v21, v21
	v_fmac_f32_e32 v227, v18, v18
	v_fmac_f32_e32 v228, v20, v20
	v_add_f32_e32 v227, v227, v228
	v_add_f32_e32 v225, v227, v225
	v_mov_b32_e32 v227, v225
	s_nop 1
	v_permlane16_swap_b32_e32 v225, v227
	s_waitcnt lgkmcnt(0)
	v_add_f32_e32 v225, v225, v227
	v_mov_b32_e32 v227, v225
	s_nop 1
	v_permlane32_swap_b32_e32 v225, v227
	s_and_saveexec_b64 s[8:9], s[6:7]
	s_cbranch_execz .LBB0_1199
	s_lshl_b32 s10, s31, 10
	s_add_i32 s10, s27, s10
	s_waitcnt lgkmcnt(0)
	v_add_f32_e32 v225, v225, v227
	v_lshl_add_u32 v227, v223, 4, s10
	ds_write_b32 v227, v225 offset:2560
.LBB0_1199:
	s_or_b64 exec, exec, s[8:9]
	v_mul_f32_e32 v225, v15, v15
	s_waitcnt lgkmcnt(0)
	v_mul_f32_e32 v227, v17, v17
	v_fmac_f32_e32 v225, v14, v14
	v_fmac_f32_e32 v227, v16, v16
	v_add_f32_e32 v225, v225, v227
	v_mul_f32_e32 v227, v11, v11
	v_mul_f32_e32 v228, v13, v13
	v_fmac_f32_e32 v227, v10, v10
	v_fmac_f32_e32 v228, v12, v12
	v_add_f32_e32 v227, v227, v228
	v_add_f32_e32 v225, v227, v225
	v_mul_f32_e32 v227, v7, v7
	v_mul_f32_e32 v228, v9, v9
	v_fmac_f32_e32 v227, v6, v6
	v_fmac_f32_e32 v228, v8, v8
	v_add_f32_e32 v227, v227, v228
	v_add_f32_e32 v225, v227, v225
	v_mul_f32_e32 v227, v3, v3
	v_mul_f32_e32 v228, v5, v5
	v_fmac_f32_e32 v227, v2, v2
	v_fmac_f32_e32 v228, v4, v4
	v_add_f32_e32 v227, v227, v228
	v_add_f32_e32 v225, v227, v225
	v_mov_b32_e32 v227, v225
	s_nop 1
	v_permlane16_swap_b32_e32 v225, v227
	s_waitcnt lgkmcnt(0)
	v_add_f32_e32 v225, v225, v227
	v_mov_b32_e32 v227, v225
	s_nop 1
	v_permlane32_swap_b32_e32 v225, v227
	s_and_saveexec_b64 s[8:9], s[6:7]
	s_cbranch_execz .LBB0_1201
	s_lshl_b32 s10, s31, 10
	s_add_i32 s10, s27, s10
	s_waitcnt lgkmcnt(0)
	v_add_f32_e32 v225, v225, v227
	v_lshl_add_u32 v223, v223, 4, s10
	ds_write_b32 v223, v225 offset:2816

; #define PG8_LAS __attribute__((address_space(3)))
;     __device__ __forceinline__ bool run(const f32x4 (&v)[2][2][4][2], const Unit& u, int wr, int wc, int fr, int fq, PG8_LAS unsigned char* lds, int wid, int lane) const {
;     ...
; #pragma unroll
;         for (int ai = 0; ai < 2; ++ai)
; #pragma unroll
;             for (int m = 0; m < 4; ++m) {
;                 float q = 0.f;
; #pragma unroll
;                 for (int bj = 0; bj < 2; ++bj)
; #pragma unroll
;                     for (int n = 0; n < 2; ++n) { const f32x4 d = v[ai][bj][m][n]; q += (d[0] * d[0] + d[1] * d[1]) + (d[2] * d[2] + d[3] * d[3]); }
;                 q += __shfl_xor(q, 16); q += __shfl_xor(q, 32);
;                 if (fq == 0) P[(ai * HALF + wr * 64 + m * 16 + fr) * 4 + wc] = q;
;             }
;     __device__ __forceinline__ void fused(f32x4 (&acc)[2][2][4][2], const Unit& u, int wr, int wc, int fr, int fq, PG8_LAS unsigned char* lds, int wid, int lane) const {
;         const PG8_LAS float* S = (const PG8_LAS float*)(lds + 8192);
;         const int col0 = u.pn * BM + wc * CWS + 8 * fq;
;         u32x4 pre[2][4][2];
; #pragma unroll
;         for (int ai = 0; ai < 2; ++ai)
; #pragma unroll
;             for (int m = 0; m < 4; ++m) { const size_t off = (size_t)(u.pm * BM + ai * HALF + wr * 64 + m * 16 + fr) * ldc + col0;
; #pragma unroll
;                 for (int bj = 0; bj < 2; ++bj) pre[ai][m][bj] = *(const u32x4*)(base + off + bj * CBS); }
;         f32x4 gq[2][2];
; #pragma unroll
;         for (int bj = 0; bj < 2; ++bj) { gq[bj][0] = *(const f32x4*)(gain + col0 + bj * CBS); gq[bj][1] = *(const f32x4*)(gain + col0 + bj * CBS + 4); }
.LBB0_1434:
	v_readlane_b32 s40, v241, 18
	v_readlane_b32 s52, v241, 30
	v_readlane_b32 s53, v241, 31
	v_readlane_b32 s54, v241, 32
	v_readlane_b32 s55, v241, 33
	s_mov_b64 s[16:17], s[52:53]
	s_lshl_b32 s0, s6, 8
	s_lshl_b32 s1, s5, 6
	v_lshrrev_b32_e32 v132, 1, v0
	v_mov_b32_e32 v130, s16
	s_or_b32 s0, s0, s1
	s_lshl_b32 s16, s4, 8
	v_and_or_b32 v210, v132, 24, s0
	s_add_i32 s0, s16, s38
	v_or_b32_e32 v132, s0, v1
	v_ashrrev_i32_e32 v211, 31, v210
	v_ashrrev_i32_e32 v133, 31, v132
	v_lshl_add_u64 v[134:135], v[210:211], 1, s[12:13]
	v_lshlrev_b64 v[136:137], 11, v[132:133]
	v_lshl_add_u64 v[136:137], v[134:135], 0, v[136:137]
	s_barrier
	global_load_dwordx4 v[206:209], v[136:137], off
	global_load_dwordx4 v[202:205], v[136:137], off offset:64
	v_or_b32_e32 v136, 16, v132
	v_ashrrev_i32_e32 v137, 31, v136
	v_lshlrev_b64 v[136:137], 11, v[136:137]
	v_lshl_add_u64 v[136:137], v[134:135], 0, v[136:137]
	global_load_dwordx4 v[198:201], v[136:137], off
	global_load_dwordx4 v[194:197], v[136:137], off offset:64
	v_or_b32_e32 v136, 32, v132
	v_ashrrev_i32_e32 v137, 31, v136
	v_lshlrev_b64 v[136:137], 11, v[136:137]
	v_lshl_add_u64 v[136:137], v[134:135], 0, v[136:137]
	global_load_dwordx4 v[190:193], v[136:137], off
	global_load_dwordx4 v[186:189], v[136:137], off offset:64
	v_or_b32_e32 v136, 48, v132
	v_ashrrev_i32_e32 v137, 31, v136
	v_lshlrev_b64 v[136:137], 11, v[136:137]
	v_lshl_add_u64 v[136:137], v[134:135], 0, v[136:137]
	global_load_dwordx4 v[182:185], v[136:137], off
	global_load_dwordx4 v[178:181], v[136:137], off offset:64
	v_add_u32_e32 v136, 0x80, v132
	v_ashrrev_i32_e32 v137, 31, v136
	v_lshlrev_b64 v[136:137], 11, v[136:137]
	v_lshl_add_u64 v[136:137], v[134:135], 0, v[136:137]
	global_load_dwordx4 v[174:177], v[136:137], off
	global_load_dwordx4 v[170:173], v[136:137], off offset:64
	v_add_u32_e32 v136, 0x90, v132
	v_ashrrev_i32_e32 v137, 31, v136
	v_lshlrev_b64 v[136:137], 11, v[136:137]
	v_lshl_add_u64 v[136:137], v[134:135], 0, v[136:137]
	global_load_dwordx4 v[166:169], v[136:137], off
	global_load_dwordx4 v[162:165], v[136:137], off offset:64
	v_add_u32_e32 v136, 0xa0, v132
	v_add_u32_e32 v132, 0xb0, v132
	v_ashrrev_i32_e32 v137, 31, v136
	v_ashrrev_i32_e32 v133, 31, v132
	v_mov_b32_e32 v131, s17
	v_lshlrev_b64 v[136:137], 11, v[136:137]
	v_lshlrev_b64 v[132:133], 11, v[132:133]
	v_lshl_add_u64 v[136:137], v[134:135], 0, v[136:137]
	v_lshl_add_u64 v[132:133], v[134:135], 0, v[132:133]
	v_lshl_add_u64 v[134:135], v[210:211], 2, v[130:131]
	global_load_dwordx4 v[158:161], v[136:137], off
	global_load_dwordx4 v[154:157], v[136:137], off offset:64
	global_load_dwordx4 v[150:153], v[132:133], off
	global_load_dwordx4 v[138:141], v[132:133], off offset:64
	global_load_dwordx4 v[142:145], v[134:135], off offset:16
	global_load_dwordx4 v[146:149], v[134:135], off
	s_nop 0
	global_load_dwordx4 v[130:133], v[134:135], off offset:144
	s_nop 0
	global_load_dwordx4 v[134:137], v[134:135], off offset:128
	v_mul_f32_e32 v218, v127, v127
	v_mul_f32_e32 v219, v129, v129
	v_fmac_f32_e32 v218, v126, v126
	v_fmac_f32_e32 v219, v128, v128
	v_add_f32_e32 v218, v218, v219
	v_mul_f32_e32 v219, v123, v123
	v_mul_f32_e32 v220, v125, v125
	v_fmac_f32_e32 v219, v122, v122
	v_fmac_f32_e32 v220, v124, v124
	v_add_f32_e32 v219, v219, v220
	v_mbcnt_lo_u32_b32 v212, -1, 0
	v_add_f32_e32 v218, v219, v218
	v_mul_f32_e32 v219, v119, v119
	v_mul_f32_e32 v220, v121, v121
	v_mbcnt_hi_u32_b32 v212, -1, v212
	v_fmac_f32_e32 v219, v118, v118
	v_fmac_f32_e32 v220, v120, v120
	v_and_b32_e32 v217, 64, v212
	v_add_f32_e32 v219, v219, v220
	v_xor_b32_e32 v213, 16, v212
	v_add_u32_e32 v217, 64, v217
	v_add_f32_e32 v218, v219, v218
	v_mul_f32_e32 v219, v115, v115
	v_mul_f32_e32 v220, v117, v117
	v_cmp_lt_i32_e32 vcc, v213, v217
	v_fmac_f32_e32 v219, v114, v114
	v_fmac_f32_e32 v220, v116, v116
	v_cndmask_b32_e32 v213, v212, v213, vcc
	v_add_f32_e32 v219, v219, v220
	v_lshlrev_b32_e32 v213, 2, v213
	v_add_f32_e32 v218, v219, v218
	v_mov_b32_e32 v219, v218
	s_nop 1
	v_permlane16_swap_b32_e32 v218, v219
	v_xor_b32_e32 v220, 32, v212
	v_cmp_lt_i32_e32 vcc, v220, v217
	s_lshl_b32 s0, s5, 2
	s_add_i32 s2, s0, 0
	v_cndmask_b32_e32 v212, v212, v220, vcc
	v_lshlrev_b32_e32 v217, 2, v212
	s_waitcnt lgkmcnt(0)
	v_add_f32_e32 v218, v218, v219
	v_mov_b32_e32 v219, v218
	s_nop 1
	v_permlane32_swap_b32_e32 v218, v219
	v_and_b32_e32 v212, 63, v0
	v_cmp_gt_u32_e32 vcc, 16, v212
	v_readlane_b32 s41, v241, 19
	v_readlane_b32 s42, v241, 20
	v_readlane_b32 s43, v241, 21
	v_readlane_b32 s44, v241, 22
	v_readlane_b32 s45, v241, 23
	v_readlane_b32 s46, v241, 24
	v_readlane_b32 s47, v241, 25
	v_readlane_b32 s48, v241, 26
	v_readlane_b32 s49, v241, 27
	v_readlane_b32 s50, v241, 28
	v_readlane_b32 s51, v241, 29
	s_mov_b64 s[18:19], s[54:55]
	s_and_saveexec_b64 s[0:1], vcc
	s_cbranch_execz .LBB0_1436
	s_lshl_b32 s3, s31, 10
	s_add_i32 s3, s2, s3
	s_waitcnt lgkmcnt(0)
	v_add_f32_e32 v218, v218, v219
	v_lshl_add_u32 v219, v1, 4, s3
	ds_write_b32 v219, v218
.LBB0_1436:
	s_or_b64 exec, exec, s[0:1]
	v_mul_f32_e32 v218, v111, v111
	s_waitcnt lgkmcnt(0)
	v_mul_f32_e32 v219, v113, v113
	v_fmac_f32_e32 v218, v110, v110
	v_fmac_f32_e32 v219, v112, v112
	v_add_f32_e32 v218, v218, v219
	v_mul_f32_e32 v219, v107, v107
	v_mul_f32_e32 v220, v109, v109
	v_fmac_f32_e32 v219, v106, v106
	v_fmac_f32_e32 v220, v108, v108
	v_add_f32_e32 v219, v219, v220
	v_add_f32_e32 v218, v219, v218
	v_mul_f32_e32 v219, v103, v103
	v_mul_f32_e32 v220, v105, v105
	v_fmac_f32_e32 v219, v102, v102
	v_fmac_f32_e32 v220, v104, v104
	v_add_f32_e32 v219, v219, v220
	v_add_f32_e32 v218, v219, v218
	v_mul_f32_e32 v219, v99, v99
	v_mul_f32_e32 v220, v101, v101
	v_fmac_f32_e32 v219, v98, v98
	v_fmac_f32_e32 v220, v100, v100
	v_add_f32_e32 v219, v219, v220
	v_add_f32_e32 v218, v219, v218
	v_mov_b32_e32 v219, v218
	s_nop 1
	v_permlane16_swap_b32_e32 v218, v219
	s_waitcnt lgkmcnt(0)
	v_add_f32_e32 v218, v218, v219
	v_mov_b32_e32 v219, v218
	s_nop 1
	v_permlane32_swap_b32_e32 v218, v219
	s_and_saveexec_b64 s[0:1], vcc
	s_cbranch_execz .LBB0_1438
	s_lshl_b32 s3, s31, 10
	s_add_i32 s3, s2, s3
	s_waitcnt lgkmcnt(0)
	v_add_f32_e32 v218, v218, v219
	v_lshl_add_u32 v219, v1, 4, s3
	ds_write_b32 v219, v218 offset:256
;     __device__ __forceinline__ bool run(const f32x4 (&v)[2][2][4][2], const Unit& u, int wr, int wc, int fr, int fq, PG8_LAS unsigned char* lds, int wid, int lane) const {
;     ...
; #pragma unroll
;         for (int ai = 0; ai < 2; ++ai)
; #pragma unroll
;             for (int m = 0; m < 4; ++m) {
;                 float q = 0.f;
; #pragma unroll
;                 for (int bj = 0; bj < 2; ++bj)
; #pragma unroll
;                     for (int n = 0; n < 2; ++n) { const f32x4 d = v[ai][bj][m][n]; q += (d[0] * d[0] + d[1] * d[1]) + (d[2] * d[2] + d[3] * d[3]); }
;                 q += __shfl_xor(q, 16); q += __shfl_xor(q, 32);
;                 if (fq == 0) P[(ai * HALF + wr * 64 + m * 16 + fr) * 4 + wc] = q;
;             }
.LBB0_1438:
	s_or_b64 exec, exec, s[0:1]
	v_mul_f32_e32 v218, v95, v95
	s_waitcnt lgkmcnt(0)
	v_mul_f32_e32 v219, v97, v97
	v_fmac_f32_e32 v218, v94, v94
	v_fmac_f32_e32 v219, v96, v96
	v_add_f32_e32 v218, v218, v219
	v_mul_f32_e32 v219, v91, v91
	v_mul_f32_e32 v220, v93, v93
	v_fmac_f32_e32 v219, v90, v90
	v_fmac_f32_e32 v220, v92, v92
	v_add_f32_e32 v219, v219, v220
	v_add_f32_e32 v218, v219, v218
	v_mul_f32_e32 v219, v87, v87
	v_mul_f32_e32 v220, v89, v89
	v_fmac_f32_e32 v219, v86, v86
	v_fmac_f32_e32 v220, v88, v88
	v_add_f32_e32 v219, v219, v220
	v_add_f32_e32 v218, v219, v218
	v_mul_f32_e32 v219, v83, v83
	v_mul_f32_e32 v220, v85, v85
	v_fmac_f32_e32 v219, v82, v82
	v_fmac_f32_e32 v220, v84, v84
	v_add_f32_e32 v219, v219, v220
	v_add_f32_e32 v218, v219, v218
	v_mov_b32_e32 v219, v218
	s_nop 1
	v_permlane16_swap_b32_e32 v218, v219
	s_waitcnt lgkmcnt(0)
	v_add_f32_e32 v218, v218, v219
	v_mov_b32_e32 v219, v218
	s_nop 1
	v_permlane32_swap_b32_e32 v218, v219
	s_and_saveexec_b64 s[0:1], vcc
	s_cbranch_execz .LBB0_1440
	s_lshl_b32 s3, s31, 10
	s_add_i32 s3, s2, s3
	s_waitcnt lgkmcnt(0)
	v_add_f32_e32 v218, v218, v219
	v_lshl_add_u32 v219, v1, 4, s3
	ds_write_b32 v219, v218 offset:512
.LBB0_1440:
	s_or_b64 exec, exec, s[0:1]
	v_mul_f32_e32 v218, v79, v79
	s_waitcnt lgkmcnt(0)
	v_mul_f32_e32 v219, v81, v81
	v_fmac_f32_e32 v218, v78, v78
	v_fmac_f32_e32 v219, v80, v80
	v_add_f32_e32 v218, v218, v219
	v_mul_f32_e32 v219, v75, v75
	v_mul_f32_e32 v220, v77, v77
	v_fmac_f32_e32 v219, v74, v74
	v_fmac_f32_e32 v220, v76, v76
	v_add_f32_e32 v219, v219, v220
	v_add_f32_e32 v218, v219, v218
	v_mul_f32_e32 v219, v71, v71
	v_mul_f32_e32 v220, v73, v73
	v_fmac_f32_e32 v219, v70, v70
	v_fmac_f32_e32 v220, v72, v72
	v_add_f32_e32 v219, v219, v220
	v_add_f32_e32 v218, v219, v218
	v_mul_f32_e32 v219, v67, v67
	v_mul_f32_e32 v220, v69, v69
	v_fmac_f32_e32 v219, v66, v66
	v_fmac_f32_e32 v220, v68, v68
	v_add_f32_e32 v219, v219, v220
	v_add_f32_e32 v218, v219, v218
	v_mov_b32_e32 v219, v218
	s_nop 1
	v_permlane16_swap_b32_e32 v218, v219
	s_waitcnt lgkmcnt(0)
	v_add_f32_e32 v218, v218, v219
	v_mov_b32_e32 v219, v218
	s_nop 1
	v_permlane32_swap_b32_e32 v218, v219
	s_and_saveexec_b64 s[0:1], vcc
	s_cbranch_execz .LBB0_1442
	s_lshl_b32 s3, s31, 10
	s_add_i32 s3, s2, s3
	s_waitcnt lgkmcnt(0)
	v_add_f32_e32 v218, v218, v219
	v_lshl_add_u32 v219, v1, 4, s3
	ds_write_b32 v219, v218 offset:768
.LBB0_1442:
	s_or_b64 exec, exec, s[0:1]
	v_mul_f32_e32 v218, v63, v63
	s_waitcnt lgkmcnt(0)
	v_mul_f32_e32 v219, v65, v65
	v_fmac_f32_e32 v218, v62, v62
	v_fmac_f32_e32 v219, v64, v64
	v_add_f32_e32 v218, v218, v219
	v_mul_f32_e32 v219, v59, v59
	v_mul_f32_e32 v220, v61, v61
	v_fmac_f32_e32 v219, v58, v58
	v_fmac_f32_e32 v220, v60, v60
	v_add_f32_e32 v219, v219, v220
	v_add_f32_e32 v218, v219, v218
	v_mul_f32_e32 v219, v55, v55
	v_mul_f32_e32 v220, v57, v57
	v_fmac_f32_e32 v219, v54, v54
	v_fmac_f32_e32 v220, v56, v56
	v_add_f32_e32 v219, v219, v220
	v_add_f32_e32 v218, v219, v218
	v_mul_f32_e32 v219, v51, v51
	v_mul_f32_e32 v220, v53, v53
	v_fmac_f32_e32 v219, v50, v50
	v_fmac_f32_e32 v220, v52, v52
	v_add_f32_e32 v219, v219, v220
	v_add_f32_e32 v218, v219, v218
	v_mov_b32_e32 v219, v218
	s_nop 1
	v_permlane16_swap_b32_e32 v218, v219
	s_waitcnt lgkmcnt(0)
	v_add_f32_e32 v218, v218, v219
	v_mov_b32_e32 v219, v218
	s_nop 1
	v_permlane32_swap_b32_e32 v218, v219
	s_and_saveexec_b64 s[0:1], vcc
	s_cbranch_execz .LBB0_1444
	s_lshl_b32 s3, s31, 10
	s_add_i32 s3, s2, s3
	s_waitcnt lgkmcnt(0)
	v_add_f32_e32 v218, v218, v219
	v_lshl_add_u32 v219, v1, 4, s3
	ds_write_b32 v219, v218 offset:2048
.LBB0_1444:
	s_or_b64 exec, exec, s[0:1]
	v_mul_f32_e32 v218, v47, v47
	s_waitcnt lgkmcnt(0)
	v_mul_f32_e32 v219, v49, v49
	v_fmac_f32_e32 v218, v46, v46
	v_fmac_f32_e32 v219, v48, v48
	v_add_f32_e32 v218, v218, v219
	v_mul_f32_e32 v219, v43, v43
	v_mul_f32_e32 v220, v45, v45
	v_fmac_f32_e32 v219, v42, v42
	v_fmac_f32_e32 v220, v44, v44
	v_add_f32_e32 v219, v219, v220
	v_add_f32_e32 v218, v219, v218
	v_mul_f32_e32 v219, v39, v39
	v_mul_f32_e32 v220, v41, v41
	v_fmac_f32_e32 v219, v38, v38
	v_fmac_f32_e32 v220, v40, v40
	v_add_f32_e32 v219, v219, v220
	v_add_f32_e32 v218, v219, v218
	v_mul_f32_e32 v219, v35, v35
	v_mul_f32_e32 v220, v37, v37
	v_fmac_f32_e32 v219, v34, v34
	v_fmac_f32_e32 v220, v36, v36
	v_add_f32_e32 v219, v219, v220
	v_add_f32_e32 v218, v219, v218
	v_mov_b32_e32 v219, v218
	s_nop 1
	v_permlane16_swap_b32_e32 v218, v219
	s_waitcnt lgkmcnt(0)
	v_add_f32_e32 v218, v218, v219
	v_mov_b32_e32 v219, v218
	s_nop 1
	v_permlane32_swap_b32_e32 v218, v219
	s_and_saveexec_b64 s[0:1], vcc
	s_cbranch_execz .LBB0_1446
	s_lshl_b32 s3, s31, 10
	s_add_i32 s3, s2, s3
	s_waitcnt lgkmcnt(0)
	v_add_f32_e32 v218, v218, v219
	v_lshl_add_u32 v219, v1, 4, s3
	ds_write_b32 v219, v218 offset:2304
.LBB0_1446:
	s_or_b64 exec, exec, s[0:1]
	v_mul_f32_e32 v218, v31, v31
	s_waitcnt lgkmcnt(0)
	v_mul_f32_e32 v219, v33, v33
	v_fmac_f32_e32 v218, v30, v30
	v_fmac_f32_e32 v219, v32, v32
	v_add_f32_e32 v218, v218, v219
	v_mul_f32_e32 v219, v27, v27
	v_mul_f32_e32 v220, v29, v29
	v_fmac_f32_e32 v219, v26, v26
	v_fmac_f32_e32 v220, v28, v28
	v_add_f32_e32 v219, v219, v220
	v_add_f32_e32 v218, v219, v218
	v_mul_f32_e32 v219, v23, v23
	v_mul_f32_e32 v220, v25, v25
	v_fmac_f32_e32 v219, v22, v22
	v_fmac_f32_e32 v220, v24, v24
	v_add_f32_e32 v219, v219, v220
	v_add_f32_e32 v218, v219, v218
	v_mul_f32_e32 v219, v19, v19
	v_mul_f32_e32 v220, v21, v21
	v_fmac_f32_e32 v219, v18, v18
	v_fmac_f32_e32 v220, v20, v20
	v_add_f32_e32 v219, v219, v220
	v_add_f32_e32 v218, v219, v218
	v_mov_b32_e32 v219, v218
	s_nop 1
	v_permlane16_swap_b32_e32 v218, v219
	s_waitcnt lgkmcnt(0)
	v_add_f32_e32 v218, v218, v219
	v_mov_b32_e32 v219, v218
	s_nop 1
	v_permlane32_swap_b32_e32 v218, v219
	s_and_saveexec_b64 s[0:1], vcc
	s_cbranch_execz .LBB0_1448
	s_lshl_b32 s3, s31, 10
	s_add_i32 s3, s2, s3
	s_waitcnt lgkmcnt(0)
	v_add_f32_e32 v218, v218, v219
	v_lshl_add_u32 v219, v1, 4, s3
	ds_write_b32 v219, v218 offset:2560
